# GATEMUL epilogue: gate and previous-sum loads issued in two batches instead of 16 to 32 serial load-wait steps
# speedup vs baseline: 1.0095x; 1.0077x over previous
;     __device__ __forceinline__ void operator()(const f32x4 (&acc)[2][2][4][2], const Unit& u, int wr, int wc, int fr, int fq) const {
;     ...
;                         if constexpr (MODE == EPI_GATEMUL) {
;                             const u32x4 gw = *(const u32x4*)(G + off); v0 = v0 * bscale; v1 = v1 * bscale;
;                             v0[0] *= bflo(gw.x); v0[1] *= bfhi(gw.x); v0[2] *= bflo(gw.y); v0[3] *= bfhi(gw.y);
;                             v1[0] *= bflo(gw.z); v1[1] *= bfhi(gw.z); v1[2] *= bflo(gw.w); v1[3] *= bfhi(gw.w);
;                             if (!first) {
;                                 const u32x4 ow = *(const u32x4*)(O + off);
;                                 v0[0] += bflo(ow.x); v0[1] += bfhi(ow.x); v0[2] += bflo(ow.y); v0[3] += bfhi(ow.y);
;                                 v1[0] += bflo(ow.z); v1[1] += bfhi(ow.z); v1[2] += bflo(ow.w); v1[3] += bfhi(ow.w);
;                             }
.LBB0_626:
	v_lshl_add_u32 v132, s52, 8, v168
	v_lshl_or_b32 v192, s40, 8, v170
	v_ashrrev_i32_e32 v133, 31, v132
	v_ashrrev_i32_e32 v193, 31, v192
	v_lshlrev_b64 v[132:133], 10, v[132:133]
	v_lshl_add_u64 v[132:133], v[132:133], 0, v[192:193]
	v_lshl_add_u64 v[130:131], v[132:133], 1, s[24:25]
	v_lshl_add_u64 v[192:193], v[132:133], 1, s[28:29]
	global_load_dwordx4 v[198:201], v[130:131], off
	global_load_dwordx4 v[202:205], v[130:131], off offset:256
	s_mov_b64 s[10:11], 0x8000
	v_lshl_add_u64 v[132:133], v[130:131], 0, s[10:11]
	global_load_dwordx4 v[206:209], v[132:133], off
	global_load_dwordx4 v[210:213], v[132:133], off offset:256
	s_mov_b64 s[10:11], 0x10000
	v_lshl_add_u64 v[132:133], v[130:131], 0, s[10:11]
	global_load_dwordx4 v[214:217], v[132:133], off
	global_load_dwordx4 v[218:221], v[132:133], off offset:256
	s_mov_b64 s[10:11], 0x18000
	v_lshl_add_u64 v[132:133], v[130:131], 0, s[10:11]
	global_load_dwordx4 v[222:225], v[132:133], off
	global_load_dwordx4 v[226:229], v[132:133], off offset:256
	s_andn2_b64 vcc, exec, s[0:1]
	s_cbranch_vccnz .Lgma_nold0
	global_load_dwordx4 v[230:233], v[192:193], off
	global_load_dwordx4 v[234:237], v[192:193], off offset:256
	s_mov_b64 s[10:11], 0x8000
	v_lshl_add_u64 v[172:173], v[192:193], 0, s[10:11]
	global_load_dwordx4 v[238:241], v[172:173], off
	global_load_dwordx4 v[242:245], v[172:173], off offset:256
	s_mov_b64 s[10:11], 0x10000
	v_lshl_add_u64 v[172:173], v[192:193], 0, s[10:11]
	global_load_dwordx4 v[246:249], v[172:173], off
	global_load_dwordx4 v[186:189], v[172:173], off offset:256
	s_mov_b64 s[10:11], 0x18000
	v_lshl_add_u64 v[172:173], v[192:193], 0, s[10:11]
	global_load_dwordx4 v[160:163], v[172:173], off
	global_load_dwordx4 v[164:167], v[172:173], off offset:256
.Lgma_nold0:
	s_waitcnt vmcnt(0)
	v_lshlrev_b32_e32 v172, 16, v198
	v_and_b32_e32 v173, 0xffff0000, v198
	v_pk_mul_f32 v[126:127], v[126:127], v[172:173]
	v_lshlrev_b32_e32 v172, 16, v199
	v_and_b32_e32 v173, 0xffff0000, v199
	v_pk_mul_f32 v[128:129], v[128:129], v[172:173]
	v_lshlrev_b32_e32 v172, 16, v200
	v_and_b32_e32 v173, 0xffff0000, v200
	v_pk_mul_f32 v[122:123], v[122:123], v[172:173]
	v_lshlrev_b32_e32 v172, 16, v201
	v_and_b32_e32 v173, 0xffff0000, v201
	v_pk_mul_f32 v[124:125], v[124:125], v[172:173]
	v_lshlrev_b32_e32 v172, 16, v202
	v_and_b32_e32 v173, 0xffff0000, v202
	v_pk_mul_f32 v[118:119], v[118:119], v[172:173]
	v_lshlrev_b32_e32 v172, 16, v203
	v_and_b32_e32 v173, 0xffff0000, v203
	v_pk_mul_f32 v[120:121], v[120:121], v[172:173]
	v_lshlrev_b32_e32 v172, 16, v204
	v_and_b32_e32 v173, 0xffff0000, v204
	v_pk_mul_f32 v[114:115], v[114:115], v[172:173]
	v_lshlrev_b32_e32 v172, 16, v205
	v_and_b32_e32 v173, 0xffff0000, v205
	v_pk_mul_f32 v[116:117], v[116:117], v[172:173]
	v_lshlrev_b32_e32 v172, 16, v206
	v_and_b32_e32 v173, 0xffff0000, v206
	v_pk_mul_f32 v[110:111], v[110:111], v[172:173]
	v_lshlrev_b32_e32 v172, 16, v207
	v_and_b32_e32 v173, 0xffff0000, v207
	v_pk_mul_f32 v[112:113], v[112:113], v[172:173]
	v_lshlrev_b32_e32 v172, 16, v208
	v_and_b32_e32 v173, 0xffff0000, v208
	v_pk_mul_f32 v[106:107], v[106:107], v[172:173]
	v_lshlrev_b32_e32 v172, 16, v209
	v_and_b32_e32 v173, 0xffff0000, v209
	v_pk_mul_f32 v[108:109], v[108:109], v[172:173]
	v_lshlrev_b32_e32 v172, 16, v210
	v_and_b32_e32 v173, 0xffff0000, v210
	v_pk_mul_f32 v[102:103], v[102:103], v[172:173]
	v_lshlrev_b32_e32 v172, 16, v211
	v_and_b32_e32 v173, 0xffff0000, v211
	v_pk_mul_f32 v[104:105], v[104:105], v[172:173]
	v_lshlrev_b32_e32 v172, 16, v212
	v_and_b32_e32 v173, 0xffff0000, v212
	v_pk_mul_f32 v[98:99], v[98:99], v[172:173]
	v_lshlrev_b32_e32 v172, 16, v213
	v_and_b32_e32 v173, 0xffff0000, v213
	v_pk_mul_f32 v[100:101], v[100:101], v[172:173]
	v_lshlrev_b32_e32 v172, 16, v214
	v_and_b32_e32 v173, 0xffff0000, v214
	v_pk_mul_f32 v[94:95], v[94:95], v[172:173]
	v_lshlrev_b32_e32 v172, 16, v215
	v_and_b32_e32 v173, 0xffff0000, v215
	v_pk_mul_f32 v[96:97], v[96:97], v[172:173]
	v_lshlrev_b32_e32 v172, 16, v216
	v_and_b32_e32 v173, 0xffff0000, v216
	v_pk_mul_f32 v[90:91], v[90:91], v[172:173]
	v_lshlrev_b32_e32 v172, 16, v217
	v_and_b32_e32 v173, 0xffff0000, v217
	v_pk_mul_f32 v[92:93], v[92:93], v[172:173]
	v_lshlrev_b32_e32 v172, 16, v218
	v_and_b32_e32 v173, 0xffff0000, v218
	v_pk_mul_f32 v[86:87], v[86:87], v[172:173]
	v_lshlrev_b32_e32 v172, 16, v219
	v_and_b32_e32 v173, 0xffff0000, v219
	v_pk_mul_f32 v[88:89], v[88:89], v[172:173]
	v_lshlrev_b32_e32 v172, 16, v220
	v_and_b32_e32 v173, 0xffff0000, v220
	v_pk_mul_f32 v[82:83], v[82:83], v[172:173]
	v_lshlrev_b32_e32 v172, 16, v221
	v_and_b32_e32 v173, 0xffff0000, v221
	v_pk_mul_f32 v[84:85], v[84:85], v[172:173]
	v_lshlrev_b32_e32 v172, 16, v222
	v_and_b32_e32 v173, 0xffff0000, v222
	v_pk_mul_f32 v[78:79], v[78:79], v[172:173]
	v_lshlrev_b32_e32 v172, 16, v223
	v_and_b32_e32 v173, 0xffff0000, v223
	v_pk_mul_f32 v[80:81], v[80:81], v[172:173]
	v_lshlrev_b32_e32 v172, 16, v224
	v_and_b32_e32 v173, 0xffff0000, v224
	v_pk_mul_f32 v[74:75], v[74:75], v[172:173]
	v_lshlrev_b32_e32 v172, 16, v225
	v_and_b32_e32 v173, 0xffff0000, v225
	v_pk_mul_f32 v[76:77], v[76:77], v[172:173]
	v_lshlrev_b32_e32 v172, 16, v226
	v_and_b32_e32 v173, 0xffff0000, v226
	v_pk_mul_f32 v[70:71], v[70:71], v[172:173]
	v_lshlrev_b32_e32 v172, 16, v227
	v_and_b32_e32 v173, 0xffff0000, v227
	v_pk_mul_f32 v[72:73], v[72:73], v[172:173]
	v_lshlrev_b32_e32 v172, 16, v228
	v_and_b32_e32 v173, 0xffff0000, v228
	v_pk_mul_f32 v[66:67], v[66:67], v[172:173]
	v_lshlrev_b32_e32 v172, 16, v229
	v_and_b32_e32 v173, 0xffff0000, v229
	v_pk_mul_f32 v[68:69], v[68:69], v[172:173]
	s_andn2_b64 vcc, exec, s[0:1]
	s_cbranch_vccnz .Lgma_noadd0
; __device__ __forceinline__ unsigned pkbf(float lo, float hi) { f32x2p v = {lo, hi}; bf16x2p b = __builtin_convertvector(v, bf16x2p); return __builtin_bit_cast(unsigned, b); }
;     __device__ __forceinline__ void operator()(const f32x4 (&acc)[2][2][4][2], const Unit& u, int wr, int wc, int fr, int fq) const {
;     ...
;                             if (!first) {
;                                 const u32x4 ow = *(const u32x4*)(O + off);
;                                 v0[0] += bflo(ow.x); v0[1] += bfhi(ow.x); v0[2] += bflo(ow.y); v0[3] += bfhi(ow.y);
;                                 v1[0] += bflo(ow.z); v1[1] += bfhi(ow.z); v1[2] += bflo(ow.w); v1[3] += bfhi(ow.w);
;                             }
;                         }
;                         u32x4 w; w.x = pkbf(v0[0], v0[1]); w.y = pkbf(v0[2], v0[3]); w.z = pkbf(v1[0], v1[1]); w.w = pkbf(v1[2], v1[3]);
;                         *(u32x4*)(O + off) = w;
	v_lshlrev_b32_e32 v172, 16, v230
	v_and_b32_e32 v173, 0xffff0000, v230
	v_pk_add_f32 v[126:127], v[126:127], v[172:173]
	v_lshlrev_b32_e32 v172, 16, v231
	v_and_b32_e32 v173, 0xffff0000, v231
	v_pk_add_f32 v[128:129], v[128:129], v[172:173]
	v_lshlrev_b32_e32 v172, 16, v232
	v_and_b32_e32 v173, 0xffff0000, v232
	v_pk_add_f32 v[122:123], v[122:123], v[172:173]
	v_lshlrev_b32_e32 v172, 16, v233
	v_and_b32_e32 v173, 0xffff0000, v233
	v_pk_add_f32 v[124:125], v[124:125], v[172:173]
	v_lshlrev_b32_e32 v172, 16, v234
	v_and_b32_e32 v173, 0xffff0000, v234
	v_pk_add_f32 v[118:119], v[118:119], v[172:173]
	v_lshlrev_b32_e32 v172, 16, v235
	v_and_b32_e32 v173, 0xffff0000, v235
	v_pk_add_f32 v[120:121], v[120:121], v[172:173]
	v_lshlrev_b32_e32 v172, 16, v236
	v_and_b32_e32 v173, 0xffff0000, v236
	v_pk_add_f32 v[114:115], v[114:115], v[172:173]
	v_lshlrev_b32_e32 v172, 16, v237
	v_and_b32_e32 v173, 0xffff0000, v237
	v_pk_add_f32 v[116:117], v[116:117], v[172:173]
	v_lshlrev_b32_e32 v172, 16, v238
	v_and_b32_e32 v173, 0xffff0000, v238
	v_pk_add_f32 v[110:111], v[110:111], v[172:173]
	v_lshlrev_b32_e32 v172, 16, v239
	v_and_b32_e32 v173, 0xffff0000, v239
	v_pk_add_f32 v[112:113], v[112:113], v[172:173]
	v_lshlrev_b32_e32 v172, 16, v240
	v_and_b32_e32 v173, 0xffff0000, v240
	v_pk_add_f32 v[106:107], v[106:107], v[172:173]
	v_lshlrev_b32_e32 v172, 16, v241
	v_and_b32_e32 v173, 0xffff0000, v241
	v_pk_add_f32 v[108:109], v[108:109], v[172:173]
	v_lshlrev_b32_e32 v172, 16, v242
	v_and_b32_e32 v173, 0xffff0000, v242
	v_pk_add_f32 v[102:103], v[102:103], v[172:173]
	v_lshlrev_b32_e32 v172, 16, v243
	v_and_b32_e32 v173, 0xffff0000, v243
	v_pk_add_f32 v[104:105], v[104:105], v[172:173]
	v_lshlrev_b32_e32 v172, 16, v244
	v_and_b32_e32 v173, 0xffff0000, v244
	v_pk_add_f32 v[98:99], v[98:99], v[172:173]
	v_lshlrev_b32_e32 v172, 16, v245
	v_and_b32_e32 v173, 0xffff0000, v245
	v_pk_add_f32 v[100:101], v[100:101], v[172:173]
	v_lshlrev_b32_e32 v172, 16, v246
	v_and_b32_e32 v173, 0xffff0000, v246
	v_pk_add_f32 v[94:95], v[94:95], v[172:173]
	v_lshlrev_b32_e32 v172, 16, v247
	v_and_b32_e32 v173, 0xffff0000, v247
	v_pk_add_f32 v[96:97], v[96:97], v[172:173]
	v_lshlrev_b32_e32 v172, 16, v248
	v_and_b32_e32 v173, 0xffff0000, v248
	v_pk_add_f32 v[90:91], v[90:91], v[172:173]
	v_lshlrev_b32_e32 v172, 16, v249
	v_and_b32_e32 v173, 0xffff0000, v249
	v_pk_add_f32 v[92:93], v[92:93], v[172:173]
	v_lshlrev_b32_e32 v172, 16, v186
	v_and_b32_e32 v173, 0xffff0000, v186
	v_pk_add_f32 v[86:87], v[86:87], v[172:173]
	v_lshlrev_b32_e32 v172, 16, v187
	v_and_b32_e32 v173, 0xffff0000, v187
	v_pk_add_f32 v[88:89], v[88:89], v[172:173]
	v_lshlrev_b32_e32 v172, 16, v188
	v_and_b32_e32 v173, 0xffff0000, v188
	v_pk_add_f32 v[82:83], v[82:83], v[172:173]
	v_lshlrev_b32_e32 v172, 16, v189
	v_and_b32_e32 v173, 0xffff0000, v189
	v_pk_add_f32 v[84:85], v[84:85], v[172:173]
	v_lshlrev_b32_e32 v172, 16, v160
	v_and_b32_e32 v173, 0xffff0000, v160
	v_pk_add_f32 v[78:79], v[78:79], v[172:173]
	v_lshlrev_b32_e32 v172, 16, v161
	v_and_b32_e32 v173, 0xffff0000, v161
	v_pk_add_f32 v[80:81], v[80:81], v[172:173]
	v_lshlrev_b32_e32 v172, 16, v162
	v_and_b32_e32 v173, 0xffff0000, v162
	v_pk_add_f32 v[74:75], v[74:75], v[172:173]
	v_lshlrev_b32_e32 v172, 16, v163
	v_and_b32_e32 v173, 0xffff0000, v163
	v_pk_add_f32 v[76:77], v[76:77], v[172:173]
	v_lshlrev_b32_e32 v172, 16, v164
	v_and_b32_e32 v173, 0xffff0000, v164
	v_pk_add_f32 v[70:71], v[70:71], v[172:173]
	v_lshlrev_b32_e32 v172, 16, v165
	v_and_b32_e32 v173, 0xffff0000, v165
	v_pk_add_f32 v[72:73], v[72:73], v[172:173]
	v_lshlrev_b32_e32 v172, 16, v166
	v_and_b32_e32 v173, 0xffff0000, v166
	v_pk_add_f32 v[66:67], v[66:67], v[172:173]
	v_lshlrev_b32_e32 v172, 16, v167
	v_and_b32_e32 v173, 0xffff0000, v167
	v_pk_add_f32 v[68:69], v[68:69], v[172:173]
.Lgma_noadd0:
	v_cvt_pk_bf16_f32 v126, v126, v127
	v_cvt_pk_bf16_f32 v127, v128, v129
	v_cvt_pk_bf16_f32 v128, v122, v123
	v_cvt_pk_bf16_f32 v129, v124, v125
	v_cvt_pk_bf16_f32 v118, v118, v119
	v_cvt_pk_bf16_f32 v119, v120, v121
	v_cvt_pk_bf16_f32 v120, v114, v115
	v_cvt_pk_bf16_f32 v121, v116, v117
	v_cvt_pk_bf16_f32 v110, v110, v111
	v_cvt_pk_bf16_f32 v111, v112, v113
	v_cvt_pk_bf16_f32 v112, v106, v107
	v_cvt_pk_bf16_f32 v113, v108, v109
	v_cvt_pk_bf16_f32 v102, v102, v103
	v_cvt_pk_bf16_f32 v103, v104, v105
	v_cvt_pk_bf16_f32 v104, v98, v99
	v_cvt_pk_bf16_f32 v105, v100, v101
	v_cvt_pk_bf16_f32 v94, v94, v95
	v_cvt_pk_bf16_f32 v95, v96, v97
	v_cvt_pk_bf16_f32 v96, v90, v91
	v_cvt_pk_bf16_f32 v97, v92, v93
	v_cvt_pk_bf16_f32 v86, v86, v87
	v_cvt_pk_bf16_f32 v87, v88, v89
	v_cvt_pk_bf16_f32 v88, v82, v83
	v_cvt_pk_bf16_f32 v89, v84, v85
	v_cvt_pk_bf16_f32 v78, v78, v79
	v_cvt_pk_bf16_f32 v79, v80, v81
	v_cvt_pk_bf16_f32 v80, v74, v75
	v_cvt_pk_bf16_f32 v81, v76, v77
	v_cvt_pk_bf16_f32 v70, v70, v71
	v_cvt_pk_bf16_f32 v71, v72, v73
	v_cvt_pk_bf16_f32 v72, v66, v67
	v_cvt_pk_bf16_f32 v73, v68, v69
	s_mov_b64 s[10:11], 0x40000
	v_lshl_add_u64 v[132:133], v[130:131], 0, s[10:11]
	global_load_dwordx4 v[198:201], v[132:133], off
	global_load_dwordx4 v[202:205], v[132:133], off offset:256
	s_mov_b64 s[10:11], 0x48000
	v_lshl_add_u64 v[132:133], v[130:131], 0, s[10:11]
	global_load_dwordx4 v[206:209], v[132:133], off
	global_load_dwordx4 v[210:213], v[132:133], off offset:256
	s_mov_b64 s[10:11], 0x50000
	v_lshl_add_u64 v[132:133], v[130:131], 0, s[10:11]
	global_load_dwordx4 v[214:217], v[132:133], off
	global_load_dwordx4 v[218:221], v[132:133], off offset:256
	s_mov_b64 s[10:11], 0x58000
	v_lshl_add_u64 v[132:133], v[130:131], 0, s[10:11]
	global_load_dwordx4 v[222:225], v[132:133], off
	global_load_dwordx4 v[226:229], v[132:133], off offset:256
	s_andn2_b64 vcc, exec, s[0:1]
	s_cbranch_vccnz .Lgma_nold1
	s_mov_b64 s[10:11], 0x40000
	v_lshl_add_u64 v[172:173], v[192:193], 0, s[10:11]
	global_load_dwordx4 v[230:233], v[172:173], off
	global_load_dwordx4 v[234:237], v[172:173], off offset:256
	s_mov_b64 s[10:11], 0x48000
	v_lshl_add_u64 v[172:173], v[192:193], 0, s[10:11]
	global_load_dwordx4 v[238:241], v[172:173], off
	global_load_dwordx4 v[242:245], v[172:173], off offset:256
	s_mov_b64 s[10:11], 0x50000
	v_lshl_add_u64 v[172:173], v[192:193], 0, s[10:11]
	global_load_dwordx4 v[246:249], v[172:173], off
	global_load_dwordx4 v[186:189], v[172:173], off offset:256
	s_mov_b64 s[10:11], 0x58000
	v_lshl_add_u64 v[172:173], v[192:193], 0, s[10:11]
	global_load_dwordx4 v[160:163], v[172:173], off
	global_load_dwordx4 v[164:167], v[172:173], off offset:256
; __device__ __forceinline__ unsigned pkbf(float lo, float hi) { f32x2p v = {lo, hi}; bf16x2p b = __builtin_convertvector(v, bf16x2p); return __builtin_bit_cast(unsigned, b); }
;     __device__ __forceinline__ void operator()(const f32x4 (&acc)[2][2][4][2], const Unit& u, int wr, int wc, int fr, int fq) const {
;     ...
;                         if constexpr (MODE == EPI_GATEMUL) {
;                             const u32x4 gw = *(const u32x4*)(G + off); v0 = v0 * bscale; v1 = v1 * bscale;
;                             v0[0] *= bflo(gw.x); v0[1] *= bfhi(gw.x); v0[2] *= bflo(gw.y); v0[3] *= bfhi(gw.y);
;                             v1[0] *= bflo(gw.z); v1[1] *= bfhi(gw.z); v1[2] *= bflo(gw.w); v1[3] *= bfhi(gw.w);
;                             if (!first) {
;                                 const u32x4 ow = *(const u32x4*)(O + off);
;                                 v0[0] += bflo(ow.x); v0[1] += bfhi(ow.x); v0[2] += bflo(ow.y); v0[3] += bfhi(ow.y);
;                                 v1[0] += bflo(ow.z); v1[1] += bfhi(ow.z); v1[2] += bflo(ow.w); v1[3] += bfhi(ow.w);
;                             }
;                         }
;                         u32x4 w; w.x = pkbf(v0[0], v0[1]); w.y = pkbf(v0[2], v0[3]); w.z = pkbf(v1[0], v1[1]); w.w = pkbf(v1[2], v1[3]);
;                         *(u32x4*)(O + off) = w;
.Lgma_nold1:
	global_store_dwordx4 v[192:193], v[126:129], off
	global_store_dwordx4 v[192:193], v[118:121], off offset:256
	s_mov_b64 s[10:11], 0x8000
	v_lshl_add_u64 v[172:173], v[192:193], 0, s[10:11]
	global_store_dwordx4 v[172:173], v[110:113], off
	global_store_dwordx4 v[172:173], v[102:105], off offset:256
	s_mov_b64 s[10:11], 0x10000
	v_lshl_add_u64 v[172:173], v[192:193], 0, s[10:11]
	global_store_dwordx4 v[172:173], v[94:97], off
	global_store_dwordx4 v[172:173], v[86:89], off offset:256
	s_mov_b64 s[10:11], 0x18000
	v_lshl_add_u64 v[172:173], v[192:193], 0, s[10:11]
	global_store_dwordx4 v[172:173], v[78:81], off
	global_store_dwordx4 v[172:173], v[70:73], off offset:256
	s_waitcnt vmcnt(8)
	v_lshlrev_b32_e32 v172, 16, v198
	v_and_b32_e32 v173, 0xffff0000, v198
	v_pk_mul_f32 v[62:63], v[62:63], v[172:173]
	v_lshlrev_b32_e32 v172, 16, v199
	v_and_b32_e32 v173, 0xffff0000, v199
	v_pk_mul_f32 v[64:65], v[64:65], v[172:173]
	v_lshlrev_b32_e32 v172, 16, v200
	v_and_b32_e32 v173, 0xffff0000, v200
	v_pk_mul_f32 v[58:59], v[58:59], v[172:173]
	v_lshlrev_b32_e32 v172, 16, v201
	v_and_b32_e32 v173, 0xffff0000, v201
	v_pk_mul_f32 v[60:61], v[60:61], v[172:173]
	v_lshlrev_b32_e32 v172, 16, v202
	v_and_b32_e32 v173, 0xffff0000, v202
	v_pk_mul_f32 v[54:55], v[54:55], v[172:173]
	v_lshlrev_b32_e32 v172, 16, v203
	v_and_b32_e32 v173, 0xffff0000, v203
	v_pk_mul_f32 v[56:57], v[56:57], v[172:173]
	v_lshlrev_b32_e32 v172, 16, v204
	v_and_b32_e32 v173, 0xffff0000, v204
	v_pk_mul_f32 v[50:51], v[50:51], v[172:173]
	v_lshlrev_b32_e32 v172, 16, v205
	v_and_b32_e32 v173, 0xffff0000, v205
	v_pk_mul_f32 v[52:53], v[52:53], v[172:173]
	v_lshlrev_b32_e32 v172, 16, v206
	v_and_b32_e32 v173, 0xffff0000, v206
	v_pk_mul_f32 v[46:47], v[46:47], v[172:173]
	v_lshlrev_b32_e32 v172, 16, v207
	v_and_b32_e32 v173, 0xffff0000, v207
	v_pk_mul_f32 v[48:49], v[48:49], v[172:173]
	v_lshlrev_b32_e32 v172, 16, v208
	v_and_b32_e32 v173, 0xffff0000, v208
	v_pk_mul_f32 v[42:43], v[42:43], v[172:173]
	v_lshlrev_b32_e32 v172, 16, v209
	v_and_b32_e32 v173, 0xffff0000, v209
	v_pk_mul_f32 v[44:45], v[44:45], v[172:173]
	v_lshlrev_b32_e32 v172, 16, v210
	v_and_b32_e32 v173, 0xffff0000, v210
	v_pk_mul_f32 v[38:39], v[38:39], v[172:173]
	v_lshlrev_b32_e32 v172, 16, v211
	v_and_b32_e32 v173, 0xffff0000, v211
	v_pk_mul_f32 v[40:41], v[40:41], v[172:173]
	v_lshlrev_b32_e32 v172, 16, v212
	v_and_b32_e32 v173, 0xffff0000, v212
	v_pk_mul_f32 v[34:35], v[34:35], v[172:173]
	v_lshlrev_b32_e32 v172, 16, v213
	v_and_b32_e32 v173, 0xffff0000, v213
	v_pk_mul_f32 v[36:37], v[36:37], v[172:173]
	v_lshlrev_b32_e32 v172, 16, v214
	v_and_b32_e32 v173, 0xffff0000, v214
	v_pk_mul_f32 v[30:31], v[30:31], v[172:173]
	v_lshlrev_b32_e32 v172, 16, v215
	v_and_b32_e32 v173, 0xffff0000, v215
	v_pk_mul_f32 v[32:33], v[32:33], v[172:173]
	v_lshlrev_b32_e32 v172, 16, v216
	v_and_b32_e32 v173, 0xffff0000, v216
	v_pk_mul_f32 v[26:27], v[26:27], v[172:173]
	v_lshlrev_b32_e32 v172, 16, v217
	v_and_b32_e32 v173, 0xffff0000, v217
	v_pk_mul_f32 v[28:29], v[28:29], v[172:173]
	v_lshlrev_b32_e32 v172, 16, v218
	v_and_b32_e32 v173, 0xffff0000, v218
	v_pk_mul_f32 v[22:23], v[22:23], v[172:173]
	v_lshlrev_b32_e32 v172, 16, v219
	v_and_b32_e32 v173, 0xffff0000, v219
	v_pk_mul_f32 v[24:25], v[24:25], v[172:173]
	v_lshlrev_b32_e32 v172, 16, v220
	v_and_b32_e32 v173, 0xffff0000, v220
	v_pk_mul_f32 v[18:19], v[18:19], v[172:173]
	v_lshlrev_b32_e32 v172, 16, v221
	v_and_b32_e32 v173, 0xffff0000, v221
	v_pk_mul_f32 v[20:21], v[20:21], v[172:173]
	v_lshlrev_b32_e32 v172, 16, v222
	v_and_b32_e32 v173, 0xffff0000, v222
	v_pk_mul_f32 v[14:15], v[14:15], v[172:173]
	v_lshlrev_b32_e32 v172, 16, v223
	v_and_b32_e32 v173, 0xffff0000, v223
	v_pk_mul_f32 v[16:17], v[16:17], v[172:173]
	v_lshlrev_b32_e32 v172, 16, v224
	v_and_b32_e32 v173, 0xffff0000, v224
	v_pk_mul_f32 v[10:11], v[10:11], v[172:173]
	v_lshlrev_b32_e32 v172, 16, v225
	v_and_b32_e32 v173, 0xffff0000, v225
	v_pk_mul_f32 v[12:13], v[12:13], v[172:173]
	v_lshlrev_b32_e32 v172, 16, v226
	v_and_b32_e32 v173, 0xffff0000, v226
	v_pk_mul_f32 v[6:7], v[6:7], v[172:173]
	v_lshlrev_b32_e32 v172, 16, v227
	v_and_b32_e32 v173, 0xffff0000, v227
	v_pk_mul_f32 v[8:9], v[8:9], v[172:173]
	v_lshlrev_b32_e32 v172, 16, v228
	v_and_b32_e32 v173, 0xffff0000, v228
	v_pk_mul_f32 v[2:3], v[2:3], v[172:173]
	v_lshlrev_b32_e32 v172, 16, v229
	v_and_b32_e32 v173, 0xffff0000, v229
	v_pk_mul_f32 v[4:5], v[4:5], v[172:173]
	s_andn2_b64 vcc, exec, s[0:1]
	s_cbranch_vccnz .Lgma_noadd1
; __device__ __forceinline__ unsigned pkbf(float lo, float hi) { f32x2p v = {lo, hi}; bf16x2p b = __builtin_convertvector(v, bf16x2p); return __builtin_bit_cast(unsigned, b); }
;     __device__ __forceinline__ void operator()(const f32x4 (&acc)[2][2][4][2], const Unit& u, int wr, int wc, int fr, int fq) const {
;     ...
;                             if (!first) {
;                                 const u32x4 ow = *(const u32x4*)(O + off);
;                                 v0[0] += bflo(ow.x); v0[1] += bfhi(ow.x); v0[2] += bflo(ow.y); v0[3] += bfhi(ow.y);
;                                 v1[0] += bflo(ow.z); v1[1] += bfhi(ow.z); v1[2] += bflo(ow.w); v1[3] += bfhi(ow.w);
;                             }
;                         }
;                         u32x4 w; w.x = pkbf(v0[0], v0[1]); w.y = pkbf(v0[2], v0[3]); w.z = pkbf(v1[0], v1[1]); w.w = pkbf(v1[2], v1[3]);
;                         *(u32x4*)(O + off) = w;
	v_lshlrev_b32_e32 v172, 16, v230
	v_and_b32_e32 v173, 0xffff0000, v230
	v_pk_add_f32 v[62:63], v[62:63], v[172:173]
	v_lshlrev_b32_e32 v172, 16, v231
	v_and_b32_e32 v173, 0xffff0000, v231
	v_pk_add_f32 v[64:65], v[64:65], v[172:173]
	v_lshlrev_b32_e32 v172, 16, v232
	v_and_b32_e32 v173, 0xffff0000, v232
	v_pk_add_f32 v[58:59], v[58:59], v[172:173]
	v_lshlrev_b32_e32 v172, 16, v233
	v_and_b32_e32 v173, 0xffff0000, v233
	v_pk_add_f32 v[60:61], v[60:61], v[172:173]
	v_lshlrev_b32_e32 v172, 16, v234
	v_and_b32_e32 v173, 0xffff0000, v234
	v_pk_add_f32 v[54:55], v[54:55], v[172:173]
	v_lshlrev_b32_e32 v172, 16, v235
	v_and_b32_e32 v173, 0xffff0000, v235
	v_pk_add_f32 v[56:57], v[56:57], v[172:173]
	v_lshlrev_b32_e32 v172, 16, v236
	v_and_b32_e32 v173, 0xffff0000, v236
	v_pk_add_f32 v[50:51], v[50:51], v[172:173]
	v_lshlrev_b32_e32 v172, 16, v237
	v_and_b32_e32 v173, 0xffff0000, v237
	v_pk_add_f32 v[52:53], v[52:53], v[172:173]
	v_lshlrev_b32_e32 v172, 16, v238
	v_and_b32_e32 v173, 0xffff0000, v238
	v_pk_add_f32 v[46:47], v[46:47], v[172:173]
	v_lshlrev_b32_e32 v172, 16, v239
	v_and_b32_e32 v173, 0xffff0000, v239
	v_pk_add_f32 v[48:49], v[48:49], v[172:173]
	v_lshlrev_b32_e32 v172, 16, v240
	v_and_b32_e32 v173, 0xffff0000, v240
	v_pk_add_f32 v[42:43], v[42:43], v[172:173]
	v_lshlrev_b32_e32 v172, 16, v241
	v_and_b32_e32 v173, 0xffff0000, v241
	v_pk_add_f32 v[44:45], v[44:45], v[172:173]
	v_lshlrev_b32_e32 v172, 16, v242
	v_and_b32_e32 v173, 0xffff0000, v242
	v_pk_add_f32 v[38:39], v[38:39], v[172:173]
	v_lshlrev_b32_e32 v172, 16, v243
	v_and_b32_e32 v173, 0xffff0000, v243
	v_pk_add_f32 v[40:41], v[40:41], v[172:173]
	v_lshlrev_b32_e32 v172, 16, v244
	v_and_b32_e32 v173, 0xffff0000, v244
	v_pk_add_f32 v[34:35], v[34:35], v[172:173]
	v_lshlrev_b32_e32 v172, 16, v245
	v_and_b32_e32 v173, 0xffff0000, v245
	v_pk_add_f32 v[36:37], v[36:37], v[172:173]
	v_lshlrev_b32_e32 v172, 16, v246
	v_and_b32_e32 v173, 0xffff0000, v246
	v_pk_add_f32 v[30:31], v[30:31], v[172:173]
	v_lshlrev_b32_e32 v172, 16, v247
	v_and_b32_e32 v173, 0xffff0000, v247
	v_pk_add_f32 v[32:33], v[32:33], v[172:173]
	v_lshlrev_b32_e32 v172, 16, v248
	v_and_b32_e32 v173, 0xffff0000, v248
	v_pk_add_f32 v[26:27], v[26:27], v[172:173]
	v_lshlrev_b32_e32 v172, 16, v249
	v_and_b32_e32 v173, 0xffff0000, v249
	v_pk_add_f32 v[28:29], v[28:29], v[172:173]
	v_lshlrev_b32_e32 v172, 16, v186
	v_and_b32_e32 v173, 0xffff0000, v186
	v_pk_add_f32 v[22:23], v[22:23], v[172:173]
	v_lshlrev_b32_e32 v172, 16, v187
	v_and_b32_e32 v173, 0xffff0000, v187
	v_pk_add_f32 v[24:25], v[24:25], v[172:173]
	v_lshlrev_b32_e32 v172, 16, v188
	v_and_b32_e32 v173, 0xffff0000, v188
	v_pk_add_f32 v[18:19], v[18:19], v[172:173]
	v_lshlrev_b32_e32 v172, 16, v189
	v_and_b32_e32 v173, 0xffff0000, v189
	v_pk_add_f32 v[20:21], v[20:21], v[172:173]
	v_lshlrev_b32_e32 v172, 16, v160
	v_and_b32_e32 v173, 0xffff0000, v160
	v_pk_add_f32 v[14:15], v[14:15], v[172:173]
	v_lshlrev_b32_e32 v172, 16, v161
	v_and_b32_e32 v173, 0xffff0000, v161
	v_pk_add_f32 v[16:17], v[16:17], v[172:173]
	v_lshlrev_b32_e32 v172, 16, v162
	v_and_b32_e32 v173, 0xffff0000, v162
	v_pk_add_f32 v[10:11], v[10:11], v[172:173]
	v_lshlrev_b32_e32 v172, 16, v163
	v_and_b32_e32 v173, 0xffff0000, v163
	v_pk_add_f32 v[12:13], v[12:13], v[172:173]
	v_lshlrev_b32_e32 v172, 16, v164
	v_and_b32_e32 v173, 0xffff0000, v164
	v_pk_add_f32 v[6:7], v[6:7], v[172:173]
	v_lshlrev_b32_e32 v172, 16, v165
	v_and_b32_e32 v173, 0xffff0000, v165
	v_pk_add_f32 v[8:9], v[8:9], v[172:173]
	v_lshlrev_b32_e32 v172, 16, v166
	v_and_b32_e32 v173, 0xffff0000, v166
	v_pk_add_f32 v[2:3], v[2:3], v[172:173]
	v_lshlrev_b32_e32 v172, 16, v167
	v_and_b32_e32 v173, 0xffff0000, v167
	v_pk_add_f32 v[4:5], v[4:5], v[172:173]
.Lgma_noadd1:
	v_cvt_pk_bf16_f32 v62, v62, v63
	v_cvt_pk_bf16_f32 v63, v64, v65
	v_cvt_pk_bf16_f32 v64, v58, v59
	v_cvt_pk_bf16_f32 v65, v60, v61
	v_cvt_pk_bf16_f32 v54, v54, v55
	v_cvt_pk_bf16_f32 v55, v56, v57
	v_cvt_pk_bf16_f32 v56, v50, v51
	v_cvt_pk_bf16_f32 v57, v52, v53
	v_cvt_pk_bf16_f32 v46, v46, v47
	v_cvt_pk_bf16_f32 v47, v48, v49
	v_cvt_pk_bf16_f32 v48, v42, v43
	v_cvt_pk_bf16_f32 v49, v44, v45
	v_cvt_pk_bf16_f32 v38, v38, v39
	v_cvt_pk_bf16_f32 v39, v40, v41
	v_cvt_pk_bf16_f32 v40, v34, v35
	v_cvt_pk_bf16_f32 v41, v36, v37
	v_cvt_pk_bf16_f32 v30, v30, v31
	v_cvt_pk_bf16_f32 v31, v32, v33
	v_cvt_pk_bf16_f32 v32, v26, v27
	v_cvt_pk_bf16_f32 v33, v28, v29
	v_cvt_pk_bf16_f32 v22, v22, v23
	v_cvt_pk_bf16_f32 v23, v24, v25
	v_cvt_pk_bf16_f32 v24, v18, v19
	v_cvt_pk_bf16_f32 v25, v20, v21
	v_cvt_pk_bf16_f32 v14, v14, v15
	v_cvt_pk_bf16_f32 v15, v16, v17
	v_cvt_pk_bf16_f32 v16, v10, v11
	v_cvt_pk_bf16_f32 v17, v12, v13
	v_cvt_pk_bf16_f32 v6, v6, v7
	v_cvt_pk_bf16_f32 v7, v8, v9
	v_cvt_pk_bf16_f32 v8, v2, v3
	v_cvt_pk_bf16_f32 v9, v4, v5
	s_mov_b64 s[10:11], 0x40000
	v_lshl_add_u64 v[172:173], v[192:193], 0, s[10:11]
	global_store_dwordx4 v[172:173], v[62:65], off
	global_store_dwordx4 v[172:173], v[54:57], off offset:256
	s_mov_b64 s[10:11], 0x48000
	v_lshl_add_u64 v[172:173], v[192:193], 0, s[10:11]
	global_store_dwordx4 v[172:173], v[46:49], off
	global_store_dwordx4 v[172:173], v[38:41], off offset:256
	s_mov_b64 s[10:11], 0x50000
	v_lshl_add_u64 v[172:173], v[192:193], 0, s[10:11]
	global_store_dwordx4 v[172:173], v[30:33], off
	global_store_dwordx4 v[172:173], v[22:25], off offset:256
	s_mov_b64 s[10:11], 0x58000
	v_lshl_add_u64 v[172:173], v[192:193], 0, s[10:11]
	global_store_dwordx4 v[172:173], v[14:17], off
	global_store_dwordx4 v[172:173], v[6:9], off offset:256
	s_mov_b64 s[62:63], s[14:15]
	s_andn2_b64 vcc, exec, s[38:39]
	s_mov_b64 s[38:39], -1
	s_cbranch_vccnz .LBB0_615
	s_andn2_b64 vcc, exec, s[20:21]
	s_cbranch_vccnz .LBB0_614
	s_barrier
	s_branch .LBB0_614
